# s5tab: skip KT iterations whose entries are never read by this sub-item; route: router-weight staging loads batched, residual row loads/stores batched
# speedup vs baseline: 1.0383x; 1.0188x over previous
; __device__ __forceinline__ void s5tab_item(const Params& p, int layer, int item, unsigned char* smem) {
;     ...
;   for (int e = tid; e < 16384; e += NT) {
;     int dir = e >> 13, j = (e >> 8) & 31, c = (e >> 4) & 15, c2 = e & 15;
;     float sum = 0.f;
; #pragma unroll 8
;     for (int pp = 0; pp < 64; pp++) {
;       float2 cc = CC[(dir * 16 + c) * 64 + pp], aa = AP[(dir * 33 + j) * 64 + pp], bb = BB[(dir * 64 + pp) * 16 + c2];
;       float wr_ = cc.x * aa.x - cc.y * aa.y, wi_ = cc.x * aa.y + cc.y * aa.x;
;       sum += wr_ * bb.x - wi_ * bb.y;
;     }
;     KT[e] = sum;
;   }
;     ...
;     for (int e = tid; e < 128 * 96; e += NT) {
;       int nl = e / 96, ch = e - nl * 96;
;       int n = sub * 128 + nl, t = n >> 4, c = n & 15;
;       float v[8];
;       if (ch < 64) {
;         int tau = ch >> 1, c0 = (ch & 1) * 8;
; #pragma unroll
;         for (int i = 0; i < 8; i++) {
;           float a = 0.f;
;           if (tau <= t) a += KT[((0 * 32 + (t - tau)) * 16 + c) * 16 + c0 + i];
;           if (tau >= t) a += KT[((1 * 32 + (tau - t)) * 16 + c) * 16 + c0 + i];
;           v[i] = a;
;         }
.LBB0_93:
	s_nop 0
	v_readfirstlane_b32 s8, v4
	s_lshr_b32 s8, s8, 9
	s_and_b32 s9, s77, 3
	s_lshl_b32 s9, s9, 2
	s_cmp_lt_u32 s8, 16
	s_cbranch_scc0 .Lkt_dir1
	s_add_i32 s9, s9, 3
	s_cmp_gt_u32 s8, s9
	s_cbranch_scc1 .Lkt_skip
	s_branch .Lkt_do
.Lkt_dir1:
	s_sub_i32 s8, s8, 16
	s_sub_i32 s9, 15, s9
	s_cmp_gt_u32 s8, s9
	s_cbranch_scc1 .Lkt_skip

; __device__ __forceinline__ void s5tab_item(const Params& p, int layer, int item, unsigned char* smem) {
;     ...
;   for (int e = tid; e < 16384; e += NT) {
;     int dir = e >> 13, j = (e >> 8) & 31, c = (e >> 4) & 15, c2 = e & 15;
;     float sum = 0.f;
; #pragma unroll 8
;     for (int pp = 0; pp < 64; pp++) {
;       float2 cc = CC[(dir * 16 + c) * 64 + pp], aa = AP[(dir * 33 + j) * 64 + pp], bb = BB[(dir * 64 + pp) * 16 + c2];
;       float wr_ = cc.x * aa.x - cc.y * aa.y, wi_ = cc.x * aa.y + cc.y * aa.x;
;       sum += wr_ * bb.x - wi_ * bb.y;
;     }
;     KT[e] = sum;
;   }
.Lkt_skip:
	v_add_u32_e32 v7, 0x200, v4
	v_cmp_lt_i32_e32 vcc, s69, v4
	v_add_u32_e32 v1, 0x800, v1
	s_or_b64 s[6:7], vcc, s[6:7]
	v_mov_b32_e32 v4, v7
	s_andn2_b64 exec, exec, s[6:7]
	s_cbranch_execnz .LBB0_93

; __device__ __forceinline__ void route_item(const Params& p, int tile, unsigned char* smem) {
;     ...
;   for (int e = tid; e < 8192; e += NT) rw[e] = p.in[38][e];
;   __syncthreads();
.LBB0_1003:
	global_load_dword v4, v[0:1], off
	global_load_dword v5, v[0:1], off offset:2048
	v_lshl_add_u64 v[0:1], v[0:1], 0, s[14:15]
	v_lshl_add_u64 v[0:1], v[0:1], 0, s[14:15]
	global_load_dword v6, v[0:1], off
	global_load_dword v7, v[0:1], off offset:2048
	v_lshl_add_u64 v[0:1], v[0:1], 0, s[14:15]
	v_lshl_add_u64 v[0:1], v[0:1], 0, s[14:15]
	global_load_dword v8, v[0:1], off
	global_load_dword v9, v[0:1], off offset:2048
	v_lshl_add_u64 v[0:1], v[0:1], 0, s[14:15]
	v_lshl_add_u64 v[0:1], v[0:1], 0, s[14:15]
	global_load_dword v10, v[0:1], off
	global_load_dword v11, v[0:1], off offset:2048
	v_lshl_add_u64 v[0:1], v[0:1], 0, s[14:15]
	v_lshl_add_u64 v[0:1], v[0:1], 0, s[14:15]
	global_load_dword v12, v[0:1], off
	global_load_dword v13, v[0:1], off offset:2048
	v_lshl_add_u64 v[0:1], v[0:1], 0, s[14:15]
	v_lshl_add_u64 v[0:1], v[0:1], 0, s[14:15]
	global_load_dword v14, v[0:1], off
	global_load_dword v15, v[0:1], off offset:2048
	v_lshl_add_u64 v[0:1], v[0:1], 0, s[14:15]
	v_lshl_add_u64 v[0:1], v[0:1], 0, s[14:15]
	global_load_dword v18, v[0:1], off
	global_load_dword v19, v[0:1], off offset:2048
	v_lshl_add_u64 v[0:1], v[0:1], 0, s[14:15]
	v_lshl_add_u64 v[0:1], v[0:1], 0, s[14:15]
	global_load_dword v20, v[0:1], off
	global_load_dword v21, v[0:1], off offset:2048
	s_waitcnt vmcnt(15)
	ds_write_b32 v3, v4
	s_waitcnt vmcnt(14)
	ds_write_b32 v3, v5 offset:2048
	s_waitcnt vmcnt(13)
	ds_write_b32 v3, v6 offset:4096
	s_waitcnt vmcnt(12)
	ds_write_b32 v3, v7 offset:6144
	s_waitcnt vmcnt(11)
	ds_write_b32 v3, v8 offset:8192
	s_waitcnt vmcnt(10)
	ds_write_b32 v3, v9 offset:10240
	s_waitcnt vmcnt(9)
	ds_write_b32 v3, v10 offset:12288
	s_waitcnt vmcnt(8)
	ds_write_b32 v3, v11 offset:14336
	s_waitcnt vmcnt(7)
	ds_write_b32 v3, v12 offset:16384
	s_waitcnt vmcnt(6)
	ds_write_b32 v3, v13 offset:18432
	s_waitcnt vmcnt(5)
	ds_write_b32 v3, v14 offset:20480
	s_waitcnt vmcnt(4)
	ds_write_b32 v3, v15 offset:22528
	s_waitcnt vmcnt(3)
	ds_write_b32 v3, v18 offset:24576
	s_waitcnt vmcnt(2)
	ds_write_b32 v3, v19 offset:26624
	s_waitcnt vmcnt(1)
	ds_write_b32 v3, v20 offset:28672
	s_waitcnt vmcnt(0)
	ds_write_b32 v3, v21 offset:30720

; #define layer launder_s(layer_)
; __device__ __forceinline__ void route_item(const Params& p, int tile, unsigned char* smem) {
;     ...
;   for (int i = 0; i < 8; i++) {
;     int rl = wave * 8 + i;
;     int row = tile * 64 + rl;
;     const float* src = (const float*)(p.ws + O_XRES) + (size_t)row * D;
;     int m = row >> 11;
;     const float* md = MOD + (size_t)(layer * 9 + m) * 6144 + 3072;
;     float4 v[4];
;     float ss = 0.f;
; #pragma unroll
;     for (int q = 0; q < 4; q++) {
;       v[q] = *(const float4*)(src + q * 256 + lane * 4);
;       ss += v[q].x * v[q].x + v[q].y * v[q].y + v[q].z * v[q].z + v[q].w * v[q].w;
;       *(float4*)(p.out + (size_t)row * D + q * 256 + lane * 4) = v[q];
;     }
;     ss = wave_sum(ss);
;     float rstd = rsqrtf(ss * (1.0f / 1024.0f) + EPS);
.LBB0_1006:
	v_mov_b64_e32 v[44:45], s[6:7]
	s_waitcnt lgkmcnt(0)
	global_load_dwordx4 v[0:3], v[44:45], off offset:336
	v_ashrrev_i32_e32 v35, 31, v34
	v_lshlrev_b64 v[46:47], 12, v[34:35]
	v_ashrrev_i32_e32 v4, 11, v34
	v_add_u32_e32 v4, 9, v4
	v_mul_hi_i32_i24_e32 v5, 0x6000, v4
	v_mul_i32_i24_e32 v4, 0x6000, v4
	v_lshl_add_u64 v[42:43], v[18:19], 0, v[4:5]
	s_mov_b64 s[10:11], 0x6c03000
	s_waitcnt vmcnt(0) lgkmcnt(0)
	v_lshl_add_u64 v[0:1], v[0:1], 0, v[46:47]
	v_lshl_add_u64 v[0:1], v[0:1], 0, v[160:161]
	global_load_dwordx4 v[12:15], v[0:1], off
	global_load_dwordx4 v[8:11], v[0:1], off offset:1024
	global_load_dwordx4 v[68:71], v[0:1], off offset:2048
	global_load_dwordx4 v[72:75], v[0:1], off offset:3072
	v_lshl_add_u64 v[2:3], v[2:3], 0, v[46:47]
	v_lshl_add_u64 v[44:45], v[2:3], 0, v[160:161]
	s_waitcnt vmcnt(3)
	global_store_dwordx4 v[44:45], v[12:15], off
	s_waitcnt vmcnt(3)
	global_store_dwordx4 v[44:45], v[8:11], off offset:1024
	s_waitcnt vmcnt(3)
	global_store_dwordx4 v[44:45], v[68:71], off offset:2048
	s_waitcnt vmcnt(3)
	global_store_dwordx4 v[44:45], v[72:75], off offset:3072
	v_mov_b32_e32 v6, v13
	v_mov_b32_e32 v4, v12
	v_mov_b32_e32 v58, v15
	v_mov_b32_e32 v7, v9
	v_mov_b32_e32 v5, v8
	v_pk_mul_f32 v[6:7], v[6:7], v[6:7]
	v_pk_fma_f32 v[4:5], v[4:5], v[4:5], v[6:7]
	v_mov_b32_e32 v6, v14
	v_mov_b32_e32 v7, v10
	v_mov_b32_e32 v59, v11
	v_pk_fma_f32 v[4:5], v[6:7], v[6:7], v[4:5]
	v_pk_fma_f32 v[58:59], v[58:59], v[58:59], v[4:5]
	v_add_f32_e32 v37, v58, v59
	v_mov_b32_e32 v4, v68
	v_mov_b32_e32 v5, v69
	v_mov_b32_e32 v6, v70
	v_mov_b32_e32 v7, v71
	v_mov_b32_e32 v0, v72
	v_mov_b32_e32 v1, v73
	v_mov_b32_e32 v2, v74
	v_mov_b32_e32 v3, v75
	v_mov_b32_e32 v60, v5
	v_mov_b32_e32 v62, v7
	v_mov_b32_e32 v46, v4
	v_mov_b32_e32 v61, v1
	v_mov_b32_e32 v47, v0
	v_pk_mul_f32 v[60:61], v[60:61], v[60:61]
	v_mov_b32_e32 v63, v3
	v_pk_fma_f32 v[46:47], v[46:47], v[46:47], v[60:61]
	v_mov_b32_e32 v60, v6
	v_mov_b32_e32 v61, v2
	v_pk_fma_f32 v[46:47], v[60:61], v[60:61], v[46:47]
	v_pk_fma_f32 v[46:47], v[62:63], v[62:63], v[46:47]
	v_lshl_add_u64 v[44:45], v[42:43], 0, s[10:11]
	v_add_f32_e32 v37, v37, v46
	s_mov_b64 s[10:11], 0x6c04000
	v_add_f32_e32 v37, v37, v47
	v_lshl_add_u64 v[46:47], v[42:43], 0, s[10:11]
	v_lshl_add_u64 v[42:43], v[44:45], 0, v[160:161]
	global_load_dwordx4 v[68:71], v[42:43], off
	v_lshl_add_u64 v[42:43], v[46:47], 0, v[160:161]
	global_load_dwordx4 v[58:61], v[24:25], off
	global_load_dwordx4 v[62:65], v[42:43], off
	ds_bpermute_b32 v39, v17, v37
	s_waitcnt lgkmcnt(0)
	v_add_f32_e32 v37, v37, v39
	ds_bpermute_b32 v39, v48, v37
	s_waitcnt lgkmcnt(0)
	v_add_f32_e32 v37, v37, v39
	ds_bpermute_b32 v39, v49, v37
	s_waitcnt lgkmcnt(0)
	v_add_f32_e32 v37, v37, v39
	ds_bpermute_b32 v39, v50, v37
	s_waitcnt lgkmcnt(0)
	v_add_f32_e32 v37, v37, v39
	ds_bpermute_b32 v39, v51, v37
	s_waitcnt lgkmcnt(0)
	v_add_f32_e32 v37, v37, v39
	ds_bpermute_b32 v39, v52, v37
	s_waitcnt lgkmcnt(0)
	v_add_f32_e32 v37, v37, v39
	v_fmamk_f32 v37, v37, 0x3a800000, v229
	v_cmp_gt_f32_e32 vcc, s89, v37
	v_mul_f32_e32 v39, 0x4b800000, v37
	s_nop 0
	v_cndmask_b32_e32 v37, v37, v39, vcc
	v_rsq_f32_e32 v37, v37
	s_nop 0
	v_mul_f32_e32 v39, 0x45800000, v37
	v_cndmask_b32_e32 v66, v37, v39, vcc
	v_mul_f32_e32 v12, v12, v66
	v_mul_f32_e32 v8, v8, v66
	v_mul_f32_e32 v4, v4, v66
	v_mul_f32_e32 v0, v0, v66
	s_waitcnt vmcnt(0)
	v_mul_f32_e32 v12, v58, v12
	v_add_f32_e32 v37, 1.0, v62
	v_fma_f32 v37, v37, v12, v68
	v_mul_f32_e32 v12, v13, v66
	v_mul_f32_e32 v12, v59, v12
	v_add_f32_e32 v13, 1.0, v63
	v_fma_f32 v39, v13, v12, v69
	v_mul_f32_e32 v12, v14, v66
	v_mul_f32_e32 v12, v60, v12
	v_add_f32_e32 v13, 1.0, v64
	v_fma_f32 v41, v12, v13, v70
	v_mul_f32_e32 v12, v15, v66
	v_lshlrev_b64 v[14:15], 11, v[34:35]
	v_mul_f32_e32 v12, v61, v12
	v_add_f32_e32 v13, 1.0, v65
	v_lshl_add_u64 v[42:43], v[32:33], 0, v[14:15]
	v_fmac_f32_e32 v71, v12, v13
	v_cvt_pk_bf16_f32 v12, v37, v39
	v_cvt_pk_bf16_f32 v13, v41, v71
	global_store_dwordx2 v[42:43], v[12:13], off
	ds_read_b128 v[12:15], v53
	ds_read_b128 v[72:75], v53 offset:16
	ds_read_b128 v[76:79], v53 offset:32
	ds_read_b128 v[80:83], v53 offset:48
	s_waitcnt lgkmcnt(0)
	v_fma_f32 v65, v37, v12, 0
	v_fma_f32 v64, v37, v13, 0
	v_fma_f32 v63, v37, v14, 0
	v_fma_f32 v62, v37, v15, 0
	v_fma_f32 v61, v37, v72, 0
	v_fma_f32 v60, v37, v73, 0
	v_fma_f32 v59, v37, v74, 0
	v_fma_f32 v58, v37, v75, 0
	ds_read_b128 v[12:15], v53 offset:64
	ds_read_b128 v[72:75], v53 offset:80
	v_fmac_f32_e32 v65, v39, v76
	v_fmac_f32_e32 v64, v39, v77
	v_fmac_f32_e32 v63, v39, v78
	v_fmac_f32_e32 v62, v39, v79
	v_fmac_f32_e32 v61, v39, v80
	v_fmac_f32_e32 v60, v39, v81
	v_fmac_f32_e32 v59, v39, v82
	v_fmac_f32_e32 v58, v39, v83
	s_waitcnt lgkmcnt(0)
	v_fmac_f32_e32 v65, v41, v12
	v_fmac_f32_e32 v64, v41, v13
	v_fmac_f32_e32 v63, v41, v14
	v_fmac_f32_e32 v62, v41, v15
	v_fmac_f32_e32 v61, v41, v72
	v_fmac_f32_e32 v60, v41, v73
	v_fmac_f32_e32 v59, v41, v74
	v_fmac_f32_e32 v58, v41, v75
	ds_read_b128 v[12:15], v53 offset:96
	ds_read_b128 v[72:75], v53 offset:112
	v_mov_b32_e32 v37, v161
	v_lshl_add_u64 v[68:69], v[44:45], 0, v[36:37]
	s_waitcnt lgkmcnt(0)
	v_fmac_f32_e32 v65, v71, v12
	v_fmac_f32_e32 v61, v71, v72
	v_fmac_f32_e32 v60, v71, v73
	v_lshl_add_u64 v[72:73], v[46:47], 0, v[36:37]
	v_fmac_f32_e32 v64, v71, v13
	v_fmac_f32_e32 v63, v71, v14
	v_fmac_f32_e32 v62, v71, v15
	v_fmac_f32_e32 v59, v71, v74
	v_fmac_f32_e32 v58, v71, v75
	global_load_dwordx4 v[12:15], v[26:27], off
	s_waitcnt vmcnt(0) lgkmcnt(0)
	v_mul_f32_e32 v8, v8, v12
	global_load_dwordx4 v[68:71], v[68:69], off
	s_nop 0
	global_load_dwordx4 v[72:75], v[72:73], off
	s_waitcnt vmcnt(0) lgkmcnt(0)
; __device__ __forceinline__ unsigned pack2(float a, float b) { unsigned r; asm("v_cvt_pk_bf16_f32 %0, %1, %2" : "=v"(r) : "v"(a), "v"(b)); return r; }
; __device__ __forceinline__ void route_item(const Params& p, int tile, unsigned char* smem) {
;     ...
; #pragma unroll
;     for (int q = 0; q < 4; q++) {
;       int cidx = q * 256 + lane * 4;
;       float4 gg = *(const float4*)(g + cidx);
;       float4 sh = *(const float4*)(md + cidx);
;       float4 sc = *(const float4*)(md + 1024 + cidx);
;       float o[4];
;       o[0] = v[q].x * rstd * gg.x * (1.f + sc.x) + sh.x;
;       o[1] = v[q].y * rstd * gg.y * (1.f + sc.y) + sh.y;
;       o[2] = v[q].z * rstd * gg.z * (1.f + sc.z) + sh.z;
;       o[3] = v[q].w * rstd * gg.w * (1.f + sc.w) + sh.w;
;       uint2 ob; ob.x = pack2(o[0], o[1]); ob.y = pack2(o[2], o[3]);
;       *(uint2*)(XN + (size_t)row * D + cidx) = ob;
; #pragma unroll
;       for (int u = 0; u < 4; u++) {
;         float4 r0 = *(const float4*)(rw + (cidx + u) * 8);
;         float4 r1 = *(const float4*)(rw + (cidx + u) * 8 + 4);
;         lg[0] += o[u] * r0.x; lg[1] += o[u] * r0.y; lg[2] += o[u] * r0.z; lg[3] += o[u] * r0.w;
;         lg[4] += o[u] * r1.x; lg[5] += o[u] * r1.y; lg[6] += o[u] * r1.z; lg[7] += o[u] * r1.w;
;       }
	v_add_f32_e32 v12, 1.0, v72
	v_fma_f32 v37, v8, v12, v68
	v_mul_f32_e32 v8, v9, v66
	v_mul_f32_e32 v8, v8, v13
	v_add_f32_e32 v9, 1.0, v73
	v_fma_f32 v39, v8, v9, v69
	v_mul_f32_e32 v8, v10, v66
	v_mul_f32_e32 v8, v8, v14
	v_add_f32_e32 v9, 1.0, v74
	v_fma_f32 v41, v8, v9, v70
	v_mul_f32_e32 v8, v11, v66
	v_mul_f32_e32 v8, v8, v15
	v_add_f32_e32 v9, 1.0, v75
	v_fmac_f32_e32 v71, v8, v9
	v_cvt_pk_bf16_f32 v8, v37, v39
	v_cvt_pk_bf16_f32 v9, v41, v71
	global_store_dwordx2 v[42:43], v[8:9], off offset:512
	ds_read_b128 v[8:11], v55
	ds_read_b128 v[12:15], v55 offset:16
	s_waitcnt lgkmcnt(0)
	v_fmac_f32_e32 v65, v37, v8
	v_fmac_f32_e32 v64, v37, v9
	v_fmac_f32_e32 v63, v37, v10
	v_fmac_f32_e32 v62, v37, v11
	v_fmac_f32_e32 v61, v37, v12
	v_fmac_f32_e32 v60, v37, v13
	v_fmac_f32_e32 v59, v37, v14
	v_fmac_f32_e32 v58, v37, v15
	ds_read_b128 v[8:11], v53 offset:8224
	ds_read_b128 v[12:15], v53 offset:8240
	ds_read_b128 v[72:75], v53 offset:8256
	ds_read_b128 v[76:79], v53 offset:8272
	s_waitcnt lgkmcnt(0)
	v_fmac_f32_e32 v65, v39, v8
	v_fmac_f32_e32 v64, v39, v9
	v_fmac_f32_e32 v63, v39, v10
	v_fmac_f32_e32 v62, v39, v11
	v_fmac_f32_e32 v61, v39, v12
	v_fmac_f32_e32 v60, v39, v13
	v_fmac_f32_e32 v59, v39, v14
	v_fmac_f32_e32 v58, v39, v15
	ds_read_b128 v[8:11], v53 offset:8288
	ds_read_b128 v[12:15], v53 offset:8304
	v_mov_b32_e32 v39, v161
	v_fmac_f32_e32 v65, v41, v72
	v_fmac_f32_e32 v64, v41, v73
	v_fmac_f32_e32 v63, v41, v74
	v_fmac_f32_e32 v62, v41, v75
	v_fmac_f32_e32 v61, v41, v76
	v_fmac_f32_e32 v60, v41, v77
	v_fmac_f32_e32 v59, v41, v78
	v_fmac_f32_e32 v58, v41, v79
	v_lshl_add_u64 v[68:69], v[46:47], 0, v[38:39]
	s_waitcnt lgkmcnt(0)
	v_fmac_f32_e32 v65, v71, v8
	v_fmac_f32_e32 v64, v71, v9
	v_fmac_f32_e32 v63, v71, v10
	v_fmac_f32_e32 v62, v71, v11
	v_fmac_f32_e32 v61, v71, v12
	v_fmac_f32_e32 v60, v71, v13
	v_fmac_f32_e32 v59, v71, v14
	v_fmac_f32_e32 v58, v71, v15
	global_load_dwordx4 v[8:11], v[28:29], off
	v_lshl_add_u64 v[12:13], v[44:45], 0, v[38:39]
	global_load_dwordx4 v[68:71], v[68:69], off
	v_mov_b32_e32 v41, v161
	global_load_dwordx4 v[12:15], v[12:13], off
	s_waitcnt vmcnt(0) lgkmcnt(0)
	v_mul_f32_e32 v4, v4, v8
	v_add_f32_e32 v8, 1.0, v68
	v_fma_f32 v12, v4, v8, v12
	v_mul_f32_e32 v4, v5, v66
	v_mul_f32_e32 v4, v4, v9
	v_add_f32_e32 v5, 1.0, v69
	v_fma_f32 v13, v4, v5, v13
	v_mul_f32_e32 v4, v6, v66
	v_mul_f32_e32 v4, v4, v10
	v_add_f32_e32 v5, 1.0, v70
	v_fma_f32 v14, v4, v5, v14
	v_mul_f32_e32 v4, v7, v66
	v_mul_f32_e32 v4, v4, v11
	v_add_f32_e32 v5, 1.0, v71
	v_fmac_f32_e32 v15, v4, v5
	v_cvt_pk_bf16_f32 v4, v12, v13
	v_cvt_pk_bf16_f32 v5, v14, v15
	global_store_dwordx2 v[42:43], v[4:5], off offset:1024
	ds_read_b128 v[4:7], v56
	ds_read_b128 v[8:11], v56 offset:16
	s_waitcnt lgkmcnt(0)
	v_fmac_f32_e32 v65, v12, v4
	v_fmac_f32_e32 v64, v12, v5
	v_fmac_f32_e32 v63, v12, v6
	v_fmac_f32_e32 v62, v12, v7
	v_fmac_f32_e32 v61, v12, v8
	v_fmac_f32_e32 v60, v12, v9
	v_fmac_f32_e32 v59, v12, v10
	v_fmac_f32_e32 v58, v12, v11
	ds_read_b128 v[4:7], v53 offset:16416
	ds_read_b128 v[8:11], v53 offset:16432
	ds_read_b128 v[68:71], v53 offset:16448
	ds_read_b128 v[72:75], v53 offset:16464
	s_waitcnt lgkmcnt(0)
	v_fmac_f32_e32 v65, v13, v4
	v_fmac_f32_e32 v64, v13, v5
	v_fmac_f32_e32 v63, v13, v6
	v_fmac_f32_e32 v62, v13, v7
	v_fmac_f32_e32 v61, v13, v8
	v_fmac_f32_e32 v60, v13, v9
	v_fmac_f32_e32 v59, v13, v10
	v_fmac_f32_e32 v58, v13, v11
	ds_read_b128 v[4:7], v53 offset:16480
	ds_read_b128 v[8:11], v53 offset:16496
	v_fmac_f32_e32 v61, v14, v72
	v_fmac_f32_e32 v60, v14, v73
	v_fmac_f32_e32 v65, v14, v68
	v_fmac_f32_e32 v64, v14, v69
	v_fmac_f32_e32 v63, v14, v70
	v_fmac_f32_e32 v62, v14, v71
	v_fmac_f32_e32 v59, v14, v74
	v_fmac_f32_e32 v58, v14, v75
	s_waitcnt lgkmcnt(0)
	v_fmac_f32_e32 v61, v15, v8
	v_fmac_f32_e32 v60, v15, v9
	v_lshl_add_u64 v[8:9], v[44:45], 0, v[40:41]
	v_lshl_add_u64 v[12:13], v[46:47], 0, v[40:41]
	v_fmac_f32_e32 v65, v15, v4
	v_fmac_f32_e32 v64, v15, v5
	v_fmac_f32_e32 v63, v15, v6
	v_fmac_f32_e32 v62, v15, v7
	v_fmac_f32_e32 v59, v15, v10
	v_fmac_f32_e32 v58, v15, v11
	global_load_dwordx4 v[4:7], v[30:31], off
	s_waitcnt vmcnt(0) lgkmcnt(0)
	v_mul_f32_e32 v0, v0, v4
	global_load_dwordx4 v[8:11], v[8:9], off
	s_nop 0
	global_load_dwordx4 v[12:15], v[12:13], off
	s_waitcnt vmcnt(0) lgkmcnt(0)
	v_add_f32_e32 v4, 1.0, v12
	v_fma_f32 v4, v0, v4, v8
	v_mul_f32_e32 v0, v1, v66
	v_mul_f32_e32 v0, v0, v5
	v_add_f32_e32 v1, 1.0, v13
	v_fma_f32 v0, v0, v1, v9
	v_mul_f32_e32 v1, v2, v66
	v_mul_f32_e32 v1, v1, v6
	v_add_f32_e32 v2, 1.0, v14
	v_fma_f32 v1, v1, v2, v10
	v_mul_f32_e32 v2, v3, v66
	v_mul_f32_e32 v2, v2, v7
	v_add_f32_e32 v3, 1.0, v15
	v_fmac_f32_e32 v11, v2, v3
	v_cvt_pk_bf16_f32 v2, v4, v0
	v_cvt_pk_bf16_f32 v3, v1, v11
	global_store_dwordx2 v[42:43], v[2:3], off offset:1536
	ds_read_b128 v[6:9], v57
	ds_read_b128 v[12:15], v57 offset:16
	s_waitcnt lgkmcnt(0)
	v_fmac_f32_e32 v65, v4, v6
	v_fmac_f32_e32 v64, v4, v7
	v_fmac_f32_e32 v63, v4, v8
	v_fmac_f32_e32 v62, v4, v9
	v_fmac_f32_e32 v61, v4, v12
	v_fmac_f32_e32 v60, v4, v13
	v_fmac_f32_e32 v59, v4, v14
	v_fmac_f32_e32 v58, v4, v15
	ds_read_b128 v[2:5], v53 offset:24608
	ds_read_b128 v[6:9], v53 offset:24624
	ds_read_b128 v[12:15], v53 offset:24640
	ds_read_b128 v[42:45], v53 offset:24656
	s_waitcnt lgkmcnt(0)
	v_fmac_f32_e32 v65, v0, v2
	v_fmac_f32_e32 v64, v0, v3
	v_fmac_f32_e32 v63, v0, v4
	v_fmac_f32_e32 v62, v0, v5
	v_fmac_f32_e32 v61, v0, v6
	v_fmac_f32_e32 v60, v0, v7
	v_fmac_f32_e32 v59, v0, v8
	v_fmac_f32_e32 v58, v0, v9
	v_fmac_f32_e32 v65, v1, v12
	v_fmac_f32_e32 v64, v1, v13
	v_fmac_f32_e32 v63, v1, v14
	v_fmac_f32_e32 v62, v1, v15
	v_fmac_f32_e32 v61, v1, v42
	v_fmac_f32_e32 v60, v1, v43
	v_fmac_f32_e32 v59, v1, v44
	v_fmac_f32_e32 v58, v1, v45
	ds_read_b128 v[0:3], v53 offset:24672
	ds_read_b128 v[4:7], v53 offset:24688
	s_waitcnt lgkmcnt(0)
; __device__ __forceinline__ void route_item(const Params& p, int tile, unsigned char* smem) {
;     ...
; #pragma unroll
;       for (int u = 0; u < 4; u++) {
;         float4 r0 = *(const float4*)(rw + (cidx + u) * 8);
;         float4 r1 = *(const float4*)(rw + (cidx + u) * 8 + 4);
;         lg[0] += o[u] * r0.x; lg[1] += o[u] * r0.y; lg[2] += o[u] * r0.z; lg[3] += o[u] * r0.w;
;         lg[4] += o[u] * r1.x; lg[5] += o[u] * r1.y; lg[6] += o[u] * r1.z; lg[7] += o[u] * r1.w;
;       }
;     }
; #pragma unroll
;     for (int e = 0; e < 8; e++) lg[e] = wave_sum(lg[e]);
	v_fmac_f32_e32 v65, v11, v0
	v_fmac_f32_e32 v64, v11, v1
	v_fmac_f32_e32 v63, v11, v2
	v_fmac_f32_e32 v62, v11, v3
	v_fmac_f32_e32 v61, v11, v4
	v_fmac_f32_e32 v60, v11, v5
	v_fmac_f32_e32 v59, v11, v6
	v_fmac_f32_e32 v58, v11, v7
	ds_bpermute_b32 v0, v17, v65
	ds_bpermute_b32 v2, v17, v64
	ds_bpermute_b32 v4, v17, v63
	ds_bpermute_b32 v6, v17, v62
	ds_bpermute_b32 v8, v17, v61
	ds_bpermute_b32 v10, v17, v60
	ds_bpermute_b32 v12, v17, v59
	ds_bpermute_b32 v14, v17, v58
	s_waitcnt lgkmcnt(0)
	v_add_f32_e32 v0, v65, v0
	v_add_f32_e32 v2, v64, v2
	v_add_f32_e32 v4, v63, v4
	v_add_f32_e32 v6, v62, v6
	v_add_f32_e32 v8, v61, v8
	v_add_f32_e32 v10, v60, v10
	v_add_f32_e32 v12, v59, v12
	v_add_f32_e32 v14, v58, v14
	ds_bpermute_b32 v1, v48, v0
	ds_bpermute_b32 v3, v48, v2
	ds_bpermute_b32 v5, v48, v4
	ds_bpermute_b32 v7, v48, v6
	ds_bpermute_b32 v9, v48, v8
	ds_bpermute_b32 v11, v48, v10
	ds_bpermute_b32 v13, v48, v12
	ds_bpermute_b32 v15, v48, v14
	s_waitcnt lgkmcnt(0)
	v_add_f32_e32 v0, v0, v1
	v_add_f32_e32 v2, v2, v3
	v_add_f32_e32 v4, v4, v5
	v_add_f32_e32 v6, v6, v7
	v_add_f32_e32 v8, v8, v9
	v_add_f32_e32 v10, v10, v11
	v_add_f32_e32 v12, v12, v13
	v_add_f32_e32 v14, v14, v15
	ds_bpermute_b32 v1, v49, v0
	ds_bpermute_b32 v3, v49, v2
	ds_bpermute_b32 v5, v49, v4
	ds_bpermute_b32 v7, v49, v6
	ds_bpermute_b32 v9, v49, v8
	ds_bpermute_b32 v11, v49, v10
	ds_bpermute_b32 v13, v49, v12
	ds_bpermute_b32 v15, v49, v14
	s_waitcnt lgkmcnt(0)
	v_add_f32_e32 v0, v0, v1
	v_add_f32_e32 v2, v2, v3
	v_add_f32_e32 v4, v4, v5
	v_add_f32_e32 v6, v6, v7
	v_add_f32_e32 v8, v8, v9
	v_add_f32_e32 v10, v10, v11
	v_add_f32_e32 v12, v12, v13
	v_add_f32_e32 v14, v14, v15
	ds_bpermute_b32 v1, v50, v0
	ds_bpermute_b32 v3, v50, v2
	ds_bpermute_b32 v5, v50, v4
	ds_bpermute_b32 v7, v50, v6
	ds_bpermute_b32 v9, v50, v8
	ds_bpermute_b32 v11, v50, v10
	ds_bpermute_b32 v13, v50, v12
	ds_bpermute_b32 v15, v50, v14
	s_waitcnt lgkmcnt(0)
	v_add_f32_e32 v0, v0, v1
	v_add_f32_e32 v2, v2, v3
	v_add_f32_e32 v4, v4, v5
	v_add_f32_e32 v6, v6, v7
	v_add_f32_e32 v8, v8, v9
	v_add_f32_e32 v10, v10, v11
	v_add_f32_e32 v12, v12, v13
	v_add_f32_e32 v14, v14, v15
	ds_bpermute_b32 v1, v51, v0
	ds_bpermute_b32 v3, v51, v2
	ds_bpermute_b32 v5, v51, v4
	ds_bpermute_b32 v7, v51, v6
	ds_bpermute_b32 v9, v51, v8
	ds_bpermute_b32 v11, v51, v10
	ds_bpermute_b32 v13, v51, v12
	ds_bpermute_b32 v15, v51, v14
	s_waitcnt lgkmcnt(0)
	v_add_f32_e32 v0, v0, v1
	v_add_f32_e32 v2, v2, v3
	v_add_f32_e32 v4, v4, v5
	v_add_f32_e32 v6, v6, v7
	v_add_f32_e32 v8, v8, v9
	v_add_f32_e32 v10, v10, v11
	v_add_f32_e32 v12, v12, v13
	v_add_f32_e32 v14, v14, v15
	ds_bpermute_b32 v1, v52, v0
	ds_bpermute_b32 v3, v52, v2
	ds_bpermute_b32 v5, v52, v4
	ds_bpermute_b32 v7, v52, v6
	ds_bpermute_b32 v9, v52, v8
	ds_bpermute_b32 v11, v52, v10
	ds_bpermute_b32 v13, v52, v12
	ds_bpermute_b32 v15, v52, v14
	s_and_saveexec_b64 s[26:27], s[8:9]
	s_cbranch_execz .LBB0_1005
; __device__ __forceinline__ void route_item(const Params& p, int tile, unsigned char* smem) {
;     ...
;     for (int e = 0; e < 8; e++) lg[e] = wave_sum(lg[e]);
;     float mx = lg[0];
; #pragma unroll
;     for (int e = 1; e < 8; e++) mx = fmaxf(mx, lg[e]);
;     float pr[8];
; #pragma unroll
;     for (int e = 0; e < 8; e++) pr[e] = expf(lg[e] - mx);
;     int e0 = 0; float p0 = pr[0];
; #pragma unroll
;     for (int e = 1; e < 8; e++) if (pr[e] > p0) { p0 = pr[e]; e0 = e; }
;     int e1 = -1; float p1 = -1.f;
; #pragma unroll
;     for (int e = 0; e < 8; e++) if (e != e0 && pr[e] > p1) { p1 = pr[e]; e1 = e; }
;     float inv = 1.0f / (p0 + p1);
;     if (lane == 0) {
;       TOKE[row] = make_int2(e0, e1);
;       TOKW[row] = make_float2(p0 * inv, p1 * inv);
;       te[rl * 2] = e0; te[rl * 2 + 1] = e1;
;     }
	s_waitcnt lgkmcnt(0)
	v_add_f32_e32 v0, v0, v1
	v_add_f32_e32 v1, v2, v3
	v_max_f32_e32 v2, v0, v1
	v_add_f32_e32 v3, v4, v5
	v_add_f32_e32 v4, v6, v7
	v_max3_f32 v2, v2, v3, v4
	v_add_f32_e32 v5, v8, v9
	v_add_f32_e32 v6, v10, v11
	v_add_f32_e32 v14, v14, v15
	v_max3_f32 v2, v2, v5, v6
	v_add_f32_e32 v7, v12, v13
	v_max3_f32 v2, v2, v7, v14
	v_sub_f32_e32 v8, v14, v2
	v_mul_f32_e32 v9, 0x3fb8aa3b, v8
	v_fma_f32 v10, v8, s55, -v9
	v_rndne_f32_e32 v11, v9
	v_fmac_f32_e32 v10, 0x32a5705f, v8
	v_sub_f32_e32 v9, v9, v11
	v_add_f32_e32 v9, v9, v10
	v_exp_f32_e32 v9, v9
	v_cvt_i32_f32_e32 v10, v11
	v_sub_f32_e32 v7, v7, v2
	v_cmp_ngt_f32_e32 vcc, s56, v8
	v_sub_f32_e32 v6, v6, v2
	v_ldexp_f32 v9, v9, v10
	v_mul_f32_e32 v10, 0x3fb8aa3b, v7
	v_fma_f32 v11, v7, s55, -v10
	v_rndne_f32_e32 v12, v10
	v_fmac_f32_e32 v11, 0x32a5705f, v7
	v_sub_f32_e32 v10, v10, v12
	v_add_f32_e32 v10, v10, v11
	v_exp_f32_e32 v10, v10
	v_cvt_i32_f32_e32 v11, v12
	v_cndmask_b32_e32 v9, 0, v9, vcc
	v_cmp_nlt_f32_e32 vcc, s54, v8
	v_sub_f32_e32 v5, v5, v2
	v_sub_f32_e32 v4, v4, v2
	v_cndmask_b32_e32 v8, v242, v9, vcc
	v_ldexp_f32 v9, v10, v11
	v_mul_f32_e32 v10, 0x3fb8aa3b, v6
	v_fma_f32 v11, v6, s55, -v10
	v_rndne_f32_e32 v12, v10
	v_fmac_f32_e32 v11, 0x32a5705f, v6
	v_sub_f32_e32 v10, v10, v12
	v_add_f32_e32 v10, v10, v11
	v_exp_f32_e32 v10, v10
	v_cvt_i32_f32_e32 v11, v12
	v_cmp_ngt_f32_e32 vcc, s56, v7
	v_sub_f32_e32 v3, v3, v2
	v_sub_f32_e32 v1, v1, v2
	v_cndmask_b32_e32 v9, 0, v9, vcc
	v_cmp_nlt_f32_e32 vcc, s54, v7
	v_sub_f32_e32 v0, v0, v2
	v_mul_f32_e32 v2, 0x3fb8aa3b, v0
	v_cndmask_b32_e32 v7, v242, v9, vcc
	v_ldexp_f32 v9, v10, v11
	v_mul_f32_e32 v10, 0x3fb8aa3b, v5
	v_fma_f32 v11, v5, s55, -v10
	v_rndne_f32_e32 v12, v10
	v_fmac_f32_e32 v11, 0x32a5705f, v5
	v_sub_f32_e32 v10, v10, v12
	v_add_f32_e32 v10, v10, v11
	v_exp_f32_e32 v10, v10
	v_cvt_i32_f32_e32 v11, v12
	v_cmp_ngt_f32_e32 vcc, s56, v6
	s_nop 1
	v_cndmask_b32_e32 v9, 0, v9, vcc
	v_cmp_nlt_f32_e32 vcc, s54, v6
	s_nop 1
	v_cndmask_b32_e32 v6, v242, v9, vcc
	v_ldexp_f32 v9, v10, v11
	v_mul_f32_e32 v10, 0x3fb8aa3b, v4
	v_fma_f32 v11, v4, s55, -v10
	v_rndne_f32_e32 v12, v10
	v_fmac_f32_e32 v11, 0x32a5705f, v4
	v_sub_f32_e32 v10, v10, v12
	v_add_f32_e32 v10, v10, v11
	v_exp_f32_e32 v10, v10
	v_cvt_i32_f32_e32 v11, v12
	v_cmp_ngt_f32_e32 vcc, s56, v5
	s_nop 1
	v_cndmask_b32_e32 v9, 0, v9, vcc
	v_cmp_nlt_f32_e32 vcc, s54, v5
	s_nop 1
	v_cndmask_b32_e32 v5, v242, v9, vcc
	v_ldexp_f32 v9, v10, v11
	v_mul_f32_e32 v10, 0x3fb8aa3b, v3
	v_fma_f32 v11, v3, s55, -v10
	v_rndne_f32_e32 v12, v10
	v_fmac_f32_e32 v11, 0x32a5705f, v3
	v_sub_f32_e32 v10, v10, v12
	v_add_f32_e32 v10, v10, v11
	v_exp_f32_e32 v10, v10
	v_cvt_i32_f32_e32 v11, v12
	v_cmp_ngt_f32_e32 vcc, s56, v4
	s_nop 1
	v_cndmask_b32_e32 v9, 0, v9, vcc
	v_cmp_nlt_f32_e32 vcc, s54, v4
	s_nop 1
	v_cndmask_b32_e32 v4, v242, v9, vcc
	v_ldexp_f32 v9, v10, v11
	v_mul_f32_e32 v10, 0x3fb8aa3b, v1
	v_fma_f32 v11, v1, s55, -v10
	v_rndne_f32_e32 v12, v10
	v_fmac_f32_e32 v11, 0x32a5705f, v1
	v_sub_f32_e32 v10, v10, v12
	v_add_f32_e32 v10, v10, v11
	v_exp_f32_e32 v10, v10
	v_cvt_i32_f32_e32 v11, v12
	v_cmp_ngt_f32_e32 vcc, s56, v3
	s_nop 1
	v_cndmask_b32_e32 v9, 0, v9, vcc
	v_cmp_nlt_f32_e32 vcc, s54, v3
	s_nop 1
	v_cndmask_b32_e32 v3, v242, v9, vcc
	v_ldexp_f32 v9, v10, v11
	v_fma_f32 v10, v0, s55, -v2
	v_rndne_f32_e32 v11, v2
	v_fmac_f32_e32 v10, 0x32a5705f, v0
	v_sub_f32_e32 v2, v2, v11
	v_add_f32_e32 v2, v2, v10
	v_exp_f32_e32 v2, v2
	v_cvt_i32_f32_e32 v10, v11
	v_cmp_ngt_f32_e32 vcc, s56, v1
	v_ldexp_f32 v2, v2, v10
	s_nop 0
	v_cndmask_b32_e32 v9, 0, v9, vcc
	v_cmp_nlt_f32_e32 vcc, s54, v1
	s_nop 1
	v_cndmask_b32_e32 v1, v242, v9, vcc
	v_cmp_ngt_f32_e32 vcc, s56, v0
	s_nop 1
	v_cndmask_b32_e32 v2, 0, v2, vcc
	v_cmp_nlt_f32_e32 vcc, s54, v0
	s_nop 1
	v_cndmask_b32_e32 v2, v242, v2, vcc
	v_cmp_gt_f32_e32 vcc, v1, v2
	v_cmp_nlt_f32_e64 s[22:23], -1.0, v2
	s_nop 0
	v_cndmask_b32_e32 v0, v2, v1, vcc
	v_cmp_gt_f32_e64 s[10:11], v3, v0
	s_nop 1
	v_cndmask_b32_e64 v0, v0, v3, s[10:11]
	v_cmp_gt_f32_e64 s[12:13], v4, v0
	s_nop 1
	v_cndmask_b32_e64 v0, v0, v4, s[12:13]
	v_cmp_gt_f32_e64 s[14:15], v5, v0
	s_nop 1
	v_cndmask_b32_e64 v0, v0, v5, s[14:15]
	v_cmp_gt_f32_e64 s[16:17], v6, v0
	s_nop 1
	v_cndmask_b32_e64 v0, v0, v6, s[16:17]
	v_cmp_gt_f32_e64 s[18:19], v7, v0
	s_nop 1
	v_cndmask_b32_e64 v9, v0, v7, s[18:19]
	v_cndmask_b32_e64 v0, 0, 1, vcc
	v_cndmask_b32_e64 v0, v0, 2, s[10:11]
	v_cndmask_b32_e64 v0, v0, 3, s[12:13]
	v_cndmask_b32_e64 v0, v0, 4, s[14:15]
	v_cndmask_b32_e64 v0, v0, 5, s[16:17]
	v_cndmask_b32_e64 v0, v0, 6, s[18:19]
	v_cmp_ngt_f32_e32 vcc, v8, v9
	s_and_b64 s[30:31], s[18:19], vcc
	s_nop 0
	v_cndmask_b32_e32 v0, 7, v0, vcc
	v_cmp_eq_u32_e64 s[20:21], 0, v0
	s_or_b64 s[34:35], s[22:23], s[20:21]
	v_cndmask_b32_e64 v2, v2, -1.0, s[34:35]
	v_cmp_ne_u32_e64 s[18:19], 1, v0
	v_cmp_gt_f32_e64 s[20:21], v1, v2
	s_and_b64 s[18:19], s[18:19], s[20:21]
	v_cndmask_b32_e64 v1, v2, v1, s[18:19]
	v_cmp_ne_u32_e64 s[16:17], 2, v0
	v_cmp_gt_f32_e64 s[20:21], v3, v1
	s_and_b64 s[16:17], s[16:17], s[20:21]
	v_cndmask_b32_e64 v1, v1, v3, s[16:17]
	v_cmp_ne_u32_e64 s[14:15], 3, v0
	v_cmp_gt_f32_e64 s[20:21], v4, v1
	s_and_b64 s[14:15], s[14:15], s[20:21]
	v_cndmask_b32_e64 v1, v1, v4, s[14:15]
	v_cmp_ne_u32_e64 s[12:13], 4, v0
	v_cmp_gt_f32_e64 s[20:21], v5, v1
	s_and_b64 s[12:13], s[12:13], s[20:21]
	v_cndmask_b32_e64 v1, v1, v5, s[12:13]
	v_cmp_ne_u32_e64 s[10:11], 5, v0
	v_cmp_gt_f32_e64 s[20:21], v6, v1
	s_and_b64 s[10:11], s[10:11], s[20:21]
	v_cndmask_b32_e64 v1, v1, v6, s[10:11]
	v_cmp_ngt_f32_e64 s[20:21], v7, v1
	s_or_b64 s[20:21], s[30:31], s[20:21]
	s_nop 0
	v_cndmask_b32_e64 v1, v7, v1, s[20:21]
	v_cmp_gt_f32_e64 s[22:23], v8, v1
	s_and_b64 s[22:23], vcc, s[22:23]
	v_cndmask_b32_e32 v7, v8, v9, vcc
	v_cndmask_b32_e64 v6, v1, v8, s[22:23]
	v_cndmask_b32_e64 v1, 0, -1, s[34:35]
	v_cndmask_b32_e64 v1, v1, 1, s[18:19]
	v_cndmask_b32_e64 v1, v1, 2, s[16:17]
	v_cndmask_b32_e64 v1, v1, 3, s[14:15]
	v_add_f32_e32 v2, v7, v6
	v_cndmask_b32_e64 v1, v1, 4, s[12:13]
	v_div_scale_f32 v3, s[12:13], v2, v2, 1.0
	v_rcp_f32_e32 v4, v3
	v_cndmask_b32_e64 v1, v1, 5, s[10:11]
	v_cndmask_b32_e64 v1, 6, v1, s[20:21]
	v_cndmask_b32_e64 v1, v1, 7, s[22:23]
	v_fma_f32 v5, -v3, v4, 1.0
	v_fmac_f32_e32 v4, v5, v4
	v_div_scale_f32 v5, vcc, 1.0, v2, 1.0
	v_mul_f32_e32 v8, v5, v4
	v_fma_f32 v9, -v3, v8, v5
	v_fmac_f32_e32 v8, v9, v4
	v_fma_f32 v3, -v3, v8, v5
	v_div_fmas_f32 v3, v3, v4, v8
	v_div_fixup_f32 v8, v3, v2, 1.0
	v_lshlrev_b64 v[2:3], 3, v[34:35]
	v_lshl_add_u64 v[4:5], v[20:21], 0, v[2:3]
	global_store_dwordx2 v[4:5], v[0:1], off
	v_mul_f32_e32 v4, v7, v8
	v_mul_f32_e32 v5, v6, v8
	v_lshl_add_u64 v[2:3], v[22:23], 0, v[2:3]
	global_store_dwordx2 v[2:3], v[4:5], off
	v_add_u32_e32 v2, s28, v54
	ds_write_b64 v2, v[0:1]
	s_branch .LBB0_1005
